# phase-16 residual epilogue: second half's 16 dependent load rounds batched into one (phases 10/14 edits kept, 8/12 batching dropped)
# speedup vs baseline: 1.0066x; 1.0066x over previous
.LBB0_2966:
	s_lshl_b32 s8, s59, 8
	v_add_u32_e32 v66, s8, v137
	v_ashrrev_i32_e32 v67, 31, v66
	s_lshl_b32 s6, s58, 8
	v_lshlrev_b64 v[66:67], 11, v[66:67]
	s_ashr_i32 s7, s6, 31
	v_lshl_add_u64 v[66:67], v[66:67], 0, s[6:7]
	v_or_b32_e32 v68, v66, v138
	v_mov_b32_e32 v69, v67
	v_lshlrev_b64 v[68:69], 1, v[68:69]
	v_lshl_add_u64 v[70:71], s[14:15], 0, v[68:69]
	v_mov_b32_e32 v212, v68
	v_add_u32_e32 v213, 0x10000, v212
	v_add_u32_e32 v214, 0x20000, v212
	v_add_u32_e32 v215, 0x30000, v212
	s_nop 1
	global_load_dwordx2 v[176:177], v212, s[14:15]
	global_load_dwordx2 v[178:179], v212, s[14:15] offset:32
	global_load_dwordx2 v[180:181], v212, s[14:15] offset:256
	global_load_dwordx2 v[182:183], v212, s[14:15] offset:288
	global_load_dwordx2 v[184:185], v213, s[14:15]
	global_load_dwordx2 v[186:187], v213, s[14:15] offset:32
	global_load_dwordx2 v[188:189], v213, s[14:15] offset:256
	global_load_dwordx2 v[190:191], v213, s[14:15] offset:288
	global_load_dwordx2 v[192:193], v214, s[14:15]
	global_load_dwordx2 v[194:195], v214, s[14:15] offset:32
	global_load_dwordx2 v[196:197], v214, s[14:15] offset:256
	global_load_dwordx2 v[198:199], v214, s[14:15] offset:288
	global_load_dwordx2 v[200:201], v215, s[14:15]
	global_load_dwordx2 v[202:203], v215, s[14:15] offset:32
	global_load_dwordx2 v[208:209], v215, s[14:15] offset:256
	global_load_dwordx2 v[210:211], v215, s[14:15] offset:288
	s_waitcnt vmcnt(0)
	v_mov_b64_e32 v[70:71], v[176:177]
	v_or_b32_e32 v72, v66, v140
	v_mov_b32_e32 v73, v67
	v_lshlrev_b64 v[72:73], 1, v[72:73]
	v_lshl_add_u64 v[68:69], s[16:17], 0, v[68:69]
	v_lshl_add_u64 v[74:75], s[14:15], 0, v[72:73]
	s_nop 0
	v_lshlrev_b32_e32 v76, 16, v70
	v_and_b32_e32 v77, 0xffff0000, v70
	v_lshlrev_b32_e32 v70, 16, v71
	v_and_b32_e32 v71, 0xffff0000, v71
	v_pk_add_f32 v[62:63], v[62:63], v[76:77]
	v_pk_add_f32 v[64:65], v[64:65], v[70:71]
	v_cvt_pk_bf16_f32 v62, v62, v63
	s_nop 0
	v_cvt_pk_bf16_f32 v63, v64, v65
	global_store_dwordx2 v[68:69], v[62:63], off
	v_mov_b64_e32 v[62:63], v[178:179]
	v_or_b32_e32 v64, v66, v142
	v_mov_b32_e32 v65, v67
	v_lshl_add_u64 v[68:69], s[16:17], 0, v[72:73]
	v_lshlrev_b64 v[64:65], 1, v[64:65]
	v_lshl_add_u64 v[70:71], s[14:15], 0, v[64:65]
	v_or_b32_e32 v66, v66, v144
	s_nop 0
	v_lshlrev_b32_e32 v72, 16, v62
	v_and_b32_e32 v73, 0xffff0000, v62
	v_lshlrev_b32_e32 v62, 16, v63
	v_and_b32_e32 v63, 0xffff0000, v63
	v_pk_add_f32 v[58:59], v[58:59], v[72:73]
	v_pk_add_f32 v[60:61], v[60:61], v[62:63]
	v_cvt_pk_bf16_f32 v58, v58, v59
	v_lshl_add_u64 v[62:63], s[16:17], 0, v[64:65]
	v_cvt_pk_bf16_f32 v59, v60, v61
	global_store_dwordx2 v[68:69], v[58:59], off
	v_mov_b64_e32 v[58:59], v[180:181]
	v_lshlrev_b64 v[60:61], 1, v[66:67]
	v_lshl_add_u64 v[64:65], s[14:15], 0, v[60:61]
	v_lshl_add_u64 v[60:61], s[16:17], 0, v[60:61]
	s_nop 0
	v_lshlrev_b32_e32 v66, 16, v58
	v_and_b32_e32 v67, 0xffff0000, v58
	v_lshlrev_b32_e32 v58, 16, v59
	v_and_b32_e32 v59, 0xffff0000, v59
	v_pk_add_f32 v[54:55], v[54:55], v[66:67]
	v_pk_add_f32 v[56:57], v[56:57], v[58:59]
	v_cvt_pk_bf16_f32 v54, v54, v55
	s_nop 0
	v_cvt_pk_bf16_f32 v55, v56, v57
	global_store_dwordx2 v[62:63], v[54:55], off
	v_mov_b64_e32 v[54:55], v[182:183]
	v_add_u32_e32 v56, s8, v139
	v_ashrrev_i32_e32 v57, 31, v56
	v_lshlrev_b64 v[56:57], 11, v[56:57]
	v_lshl_add_u64 v[56:57], v[56:57], 0, s[6:7]
	v_or_b32_e32 v58, v56, v138
	v_mov_b32_e32 v59, v57
	v_lshlrev_b64 v[58:59], 1, v[58:59]
	v_lshl_add_u64 v[62:63], s[14:15], 0, v[58:59]
	s_nop 0
	v_lshlrev_b32_e32 v64, 16, v54
	v_and_b32_e32 v65, 0xffff0000, v54
	v_lshlrev_b32_e32 v54, 16, v55
	v_and_b32_e32 v55, 0xffff0000, v55
	v_pk_add_f32 v[50:51], v[50:51], v[64:65]
	v_pk_add_f32 v[52:53], v[52:53], v[54:55]
	v_cvt_pk_bf16_f32 v50, v50, v51
	v_lshl_add_u64 v[54:55], s[16:17], 0, v[58:59]
	v_cvt_pk_bf16_f32 v51, v52, v53
	global_store_dwordx2 v[60:61], v[50:51], off
	v_mov_b64_e32 v[50:51], v[184:185]
	v_or_b32_e32 v52, v56, v140
	v_mov_b32_e32 v53, v57
	v_lshlrev_b64 v[52:53], 1, v[52:53]
	v_lshl_add_u64 v[58:59], s[14:15], 0, v[52:53]
	s_nop 0
	v_lshlrev_b32_e32 v60, 16, v50
	v_and_b32_e32 v61, 0xffff0000, v50
	v_lshlrev_b32_e32 v50, 16, v51
	v_and_b32_e32 v51, 0xffff0000, v51
	v_pk_add_f32 v[46:47], v[46:47], v[60:61]
	v_pk_add_f32 v[48:49], v[48:49], v[50:51]
	v_cvt_pk_bf16_f32 v46, v46, v47
	v_lshl_add_u64 v[50:51], s[16:17], 0, v[52:53]
	v_cvt_pk_bf16_f32 v47, v48, v49
	global_store_dwordx2 v[54:55], v[46:47], off
	v_mov_b64_e32 v[46:47], v[186:187]
	v_or_b32_e32 v48, v56, v142
	v_mov_b32_e32 v49, v57
	v_lshlrev_b64 v[48:49], 1, v[48:49]
	v_lshl_add_u64 v[52:53], s[14:15], 0, v[48:49]
	v_or_b32_e32 v56, v56, v144
	s_nop 0
	v_lshlrev_b32_e32 v54, 16, v46
	v_and_b32_e32 v55, 0xffff0000, v46
	v_lshlrev_b32_e32 v46, 16, v47
	v_and_b32_e32 v47, 0xffff0000, v47
	v_pk_add_f32 v[42:43], v[42:43], v[54:55]
	v_pk_add_f32 v[44:45], v[44:45], v[46:47]
	v_cvt_pk_bf16_f32 v42, v42, v43
	v_lshl_add_u64 v[46:47], s[16:17], 0, v[48:49]
	v_cvt_pk_bf16_f32 v43, v44, v45
	global_store_dwordx2 v[50:51], v[42:43], off
	v_mov_b64_e32 v[42:43], v[188:189]
	v_lshlrev_b64 v[44:45], 1, v[56:57]
	v_lshl_add_u64 v[48:49], s[14:15], 0, v[44:45]
	v_lshl_add_u64 v[44:45], s[16:17], 0, v[44:45]
	s_nop 0
	v_lshlrev_b32_e32 v50, 16, v42
	v_and_b32_e32 v51, 0xffff0000, v42
	v_lshlrev_b32_e32 v42, 16, v43
	v_and_b32_e32 v43, 0xffff0000, v43
	v_pk_add_f32 v[38:39], v[38:39], v[50:51]
	v_pk_add_f32 v[40:41], v[40:41], v[42:43]
	v_cvt_pk_bf16_f32 v38, v38, v39
	s_nop 0
	v_cvt_pk_bf16_f32 v39, v40, v41
	global_store_dwordx2 v[46:47], v[38:39], off
	v_mov_b64_e32 v[38:39], v[190:191]
	v_add_u32_e32 v40, s8, v141
	v_ashrrev_i32_e32 v41, 31, v40
	v_lshlrev_b64 v[40:41], 11, v[40:41]
	v_lshl_add_u64 v[40:41], v[40:41], 0, s[6:7]
	v_or_b32_e32 v42, v40, v138
	v_mov_b32_e32 v43, v41
	v_lshlrev_b64 v[42:43], 1, v[42:43]
	v_lshl_add_u64 v[46:47], s[14:15], 0, v[42:43]
	s_nop 0
	v_lshlrev_b32_e32 v48, 16, v38
	v_and_b32_e32 v49, 0xffff0000, v38
	v_lshlrev_b32_e32 v38, 16, v39
	v_and_b32_e32 v39, 0xffff0000, v39
	v_pk_add_f32 v[34:35], v[34:35], v[48:49]
	v_pk_add_f32 v[36:37], v[36:37], v[38:39]
	v_cvt_pk_bf16_f32 v34, v34, v35
	v_lshl_add_u64 v[38:39], s[16:17], 0, v[42:43]
	v_cvt_pk_bf16_f32 v35, v36, v37
	global_store_dwordx2 v[44:45], v[34:35], off
	v_mov_b64_e32 v[34:35], v[192:193]
	v_or_b32_e32 v36, v40, v140
	v_mov_b32_e32 v37, v41
	v_lshlrev_b64 v[36:37], 1, v[36:37]
	v_lshl_add_u64 v[42:43], s[14:15], 0, v[36:37]
	s_nop 0
	v_lshlrev_b32_e32 v44, 16, v34
	v_and_b32_e32 v45, 0xffff0000, v34
	v_lshlrev_b32_e32 v34, 16, v35
	v_and_b32_e32 v35, 0xffff0000, v35
	v_pk_add_f32 v[30:31], v[30:31], v[44:45]
	v_pk_add_f32 v[32:33], v[32:33], v[34:35]
	v_cvt_pk_bf16_f32 v30, v30, v31
	v_lshl_add_u64 v[34:35], s[16:17], 0, v[36:37]
	v_cvt_pk_bf16_f32 v31, v32, v33
	global_store_dwordx2 v[38:39], v[30:31], off
	v_mov_b64_e32 v[30:31], v[194:195]
	v_or_b32_e32 v32, v40, v142
	v_mov_b32_e32 v33, v41
	v_lshlrev_b64 v[32:33], 1, v[32:33]
	v_lshl_add_u64 v[36:37], s[14:15], 0, v[32:33]
	v_or_b32_e32 v40, v40, v144
	s_nop 0
	v_lshlrev_b32_e32 v38, 16, v30
	v_and_b32_e32 v39, 0xffff0000, v30
	v_lshlrev_b32_e32 v30, 16, v31
	v_and_b32_e32 v31, 0xffff0000, v31
	v_pk_add_f32 v[26:27], v[26:27], v[38:39]
	v_pk_add_f32 v[28:29], v[28:29], v[30:31]
	v_cvt_pk_bf16_f32 v26, v26, v27
	v_lshl_add_u64 v[30:31], s[16:17], 0, v[32:33]
	v_cvt_pk_bf16_f32 v27, v28, v29
	global_store_dwordx2 v[34:35], v[26:27], off
	v_mov_b64_e32 v[26:27], v[196:197]
	v_lshlrev_b64 v[28:29], 1, v[40:41]
	v_lshl_add_u64 v[32:33], s[14:15], 0, v[28:29]
	v_lshl_add_u64 v[28:29], s[16:17], 0, v[28:29]
	s_nop 0
	v_lshlrev_b32_e32 v34, 16, v26
	v_and_b32_e32 v35, 0xffff0000, v26
	v_lshlrev_b32_e32 v26, 16, v27
	v_and_b32_e32 v27, 0xffff0000, v27
	v_pk_add_f32 v[22:23], v[22:23], v[34:35]
	v_pk_add_f32 v[24:25], v[24:25], v[26:27]
	v_cvt_pk_bf16_f32 v22, v22, v23
	s_nop 0
	v_cvt_pk_bf16_f32 v23, v24, v25
	global_store_dwordx2 v[30:31], v[22:23], off
	v_mov_b64_e32 v[22:23], v[198:199]
	v_add_u32_e32 v24, s8, v143
	v_ashrrev_i32_e32 v25, 31, v24
	v_lshlrev_b64 v[24:25], 11, v[24:25]
	v_lshl_add_u64 v[24:25], v[24:25], 0, s[6:7]
	v_or_b32_e32 v26, v24, v138
	v_mov_b32_e32 v27, v25
	v_lshlrev_b64 v[26:27], 1, v[26:27]
	v_lshl_add_u64 v[30:31], s[14:15], 0, v[26:27]
	s_nop 0
	v_lshlrev_b32_e32 v32, 16, v22
	v_and_b32_e32 v33, 0xffff0000, v22
	v_lshlrev_b32_e32 v22, 16, v23
	v_and_b32_e32 v23, 0xffff0000, v23
	v_pk_add_f32 v[18:19], v[18:19], v[32:33]
	v_pk_add_f32 v[20:21], v[20:21], v[22:23]
	v_cvt_pk_bf16_f32 v18, v18, v19
	v_lshl_add_u64 v[22:23], s[16:17], 0, v[26:27]
	v_cvt_pk_bf16_f32 v19, v20, v21
	global_store_dwordx2 v[28:29], v[18:19], off
	v_mov_b64_e32 v[18:19], v[200:201]
	v_or_b32_e32 v20, v24, v140
	v_mov_b32_e32 v21, v25
	v_lshlrev_b64 v[20:21], 1, v[20:21]
	v_lshl_add_u64 v[26:27], s[14:15], 0, v[20:21]
	s_nop 0
	v_lshlrev_b32_e32 v28, 16, v18
	v_and_b32_e32 v29, 0xffff0000, v18
	v_lshlrev_b32_e32 v18, 16, v19
	v_and_b32_e32 v19, 0xffff0000, v19
	v_pk_add_f32 v[14:15], v[14:15], v[28:29]
	v_pk_add_f32 v[16:17], v[16:17], v[18:19]
	v_cvt_pk_bf16_f32 v14, v14, v15
	v_lshl_add_u64 v[18:19], s[16:17], 0, v[20:21]
	v_cvt_pk_bf16_f32 v15, v16, v17
	global_store_dwordx2 v[22:23], v[14:15], off
	v_mov_b64_e32 v[14:15], v[202:203]
	v_or_b32_e32 v16, v24, v142
	v_mov_b32_e32 v17, v25
	v_lshlrev_b64 v[16:17], 1, v[16:17]
	v_lshl_add_u64 v[20:21], s[14:15], 0, v[16:17]
	v_or_b32_e32 v24, v24, v144
	s_nop 0
	v_lshlrev_b32_e32 v22, 16, v14
	v_and_b32_e32 v23, 0xffff0000, v14
	v_lshlrev_b32_e32 v14, 16, v15
	v_and_b32_e32 v15, 0xffff0000, v15
	v_pk_add_f32 v[10:11], v[10:11], v[22:23]
	v_pk_add_f32 v[12:13], v[12:13], v[14:15]
	v_cvt_pk_bf16_f32 v10, v10, v11
	v_lshl_add_u64 v[14:15], s[16:17], 0, v[16:17]
	v_cvt_pk_bf16_f32 v11, v12, v13
	global_store_dwordx2 v[18:19], v[10:11], off
	v_mov_b64_e32 v[10:11], v[208:209]
	v_lshlrev_b64 v[12:13], 1, v[24:25]
	v_lshl_add_u64 v[16:17], s[14:15], 0, v[12:13]
	s_nop 0
	v_lshlrev_b32_e32 v18, 16, v10
	v_and_b32_e32 v19, 0xffff0000, v10
	v_lshlrev_b32_e32 v10, 16, v11
	v_and_b32_e32 v11, 0xffff0000, v11
	v_pk_add_f32 v[6:7], v[6:7], v[18:19]
	v_pk_add_f32 v[8:9], v[8:9], v[10:11]
	v_cvt_pk_bf16_f32 v6, v6, v7
	s_nop 0
	v_cvt_pk_bf16_f32 v7, v8, v9
	global_store_dwordx2 v[14:15], v[6:7], off
	v_mov_b64_e32 v[6:7], v[210:211]
	s_nop 0
	v_lshlrev_b32_e32 v8, 16, v6
	v_and_b32_e32 v9, 0xffff0000, v6
	v_lshlrev_b32_e32 v6, 16, v7
	v_and_b32_e32 v7, 0xffff0000, v7
	v_pk_add_f32 v[4:5], v[4:5], v[6:7]
	v_pk_add_f32 v[2:3], v[2:3], v[8:9]
	s_nop 0
	v_cvt_pk_bf16_f32 v2, v2, v3
	v_cvt_pk_bf16_f32 v3, v4, v5
	v_lshl_add_u64 v[4:5], s[16:17], 0, v[12:13]
	global_store_dwordx2 v[4:5], v[2:3], off
	s_and_b64 vcc, exec, s[4:5]
	s_mov_b64 s[4:5], -1
	s_cbranch_vccnz .LBB0_2873
	s_branch .LBB0_2998
